# trailing half (waves 4-7) takes s_setprio 1 at every GEMM epilogue entry (reset by the next K-loop's own flips), on top of the GLA-entry raise
# baseline (speedup 1.0000x reference)
; #define LAS __attribute__((address_space(3)))
; #define PG8_BAR __builtin_amdgcn_s_barrier()
;     ...
;         if constexpr (ALIGN_EPI) { if (wr == 0) PG8_BAR; }
;         E(acc, cur, wr, wc, fr, fq, (const LAS float*)(lds + rsoff));
.Lepi_prio_0:
	s_setprio 1
	s_branch .LBB0_87
